# barrier acquire done once per block by the polling lane before the block barrier (doc's consumer recipe); per-wave buffer_inv after the barrier removed
# speedup vs baseline: 1.3733x; 1.0355x over previous
.LBB0_98:
	s_or_b64 exec, exec, s[2:3]
	s_barrier
	s_waitcnt vmcnt(0)
